# write-through (sc1) stores in the qkprep and post streaming phases so the following grid barriers have less dirty L2 to write back (on top of ring5+DPP)
# baseline (speedup 1.0000x reference)
.Lqk_skip_n:
	s_nop 1
	v_add_f32_dpp v0, v0, v0 quad_perm:[2,3,0,1] row_mask:0xf bank_mask:0xf
	s_waitcnt lgkmcnt(0)
	s_nop 0
	s_nop 1
	v_add_f32_dpp v0, v0, v0 row_half_mirror row_mask:0xf bank_mask:0xf
	s_waitcnt lgkmcnt(0)
	s_nop 0
	s_nop 1
	v_add_f32_dpp v0, v0, v0 row_mirror row_mask:0xf bank_mask:0xf
	s_waitcnt lgkmcnt(0)
	s_nop 0
	ds_bpermute_b32 v70, v80, v0
	s_waitcnt lgkmcnt(0)
	v_add_f32_e32 v0, v0, v70
	v_mov_b32_e32 v70, v0
	s_nop 1
	v_permlane32_swap_b32_e32 v0, v70
	s_waitcnt lgkmcnt(0)
	v_add_f32_e32 v0, v0, v70
	v_fmac_f32_e32 v63, 0xbb000000, v0
	v_fmac_f32_e32 v65, 0xbb000000, v0
	v_fmac_f32_e32 v67, 0xbb000000, v0
	v_fmac_f32_e32 v69, 0xbb000000, v0
	v_fmac_f32_e32 v62, 0xbb000000, v0
	v_fmac_f32_e32 v64, 0xbb000000, v0
	v_fmac_f32_e32 v66, 0xbb000000, v0
	v_fmac_f32_e32 v68, 0xbb000000, v0
	v_mul_f32_e32 v63, v63, v63
	v_mul_f32_e32 v65, v65, v65
	v_mul_f32_e32 v67, v67, v67
	v_mul_f32_e32 v69, v69, v69
	v_fmac_f32_e32 v63, v62, v62
	v_fmac_f32_e32 v65, v64, v64
	v_fmac_f32_e32 v67, v66, v66
	v_fmac_f32_e32 v69, v68, v68
	v_add_f32_e32 v62, v63, v65
	v_add_f32_e32 v63, v67, v69
	v_add_f32_e32 v62, v62, v63
	s_nop 1
	v_add_f32_dpp v62, v62, v62 quad_perm:[1,0,3,2] row_mask:0xf bank_mask:0xf
	s_waitcnt lgkmcnt(0)
	s_nop 0
	s_nop 1
	v_add_f32_dpp v62, v62, v62 quad_perm:[2,3,0,1] row_mask:0xf bank_mask:0xf
	s_waitcnt lgkmcnt(0)
	s_nop 0
	s_nop 1
	v_add_f32_dpp v62, v62, v62 row_half_mirror row_mask:0xf bank_mask:0xf
	s_waitcnt lgkmcnt(0)
	s_nop 0
	s_nop 1
	v_add_f32_dpp v62, v62, v62 row_mirror row_mask:0xf bank_mask:0xf
	s_waitcnt lgkmcnt(0)
	s_nop 0
	ds_bpermute_b32 v63, v80, v62
	s_waitcnt lgkmcnt(0)
	v_add_f32_e32 v62, v62, v63
	ds_bpermute_b32 v63, v81, v62
	s_and_saveexec_b64 s[12:13], s[10:11]
	s_cbranch_execz .LBB0_796
	s_waitcnt lgkmcnt(0)
	v_add_f32_e32 v62, v62, v63
	v_fmamk_f32 v62, v62, 0x3b000000, v216
	v_mul_f32_e32 v63, 0x4b800000, v62
	v_cmp_gt_f32_e32 vcc, s33, v62
	v_lshl_add_u64 v[64:65], s[16:17], 0, v[52:53]
	s_nop 0
	v_cndmask_b32_e32 v62, v62, v63, vcc
	v_rsq_f32_e32 v63, v62
	v_mul_f32_e32 v62, 0x3b000000, v0
	v_mul_f32_e32 v0, 0x45800000, v63
	v_cndmask_b32_e32 v63, v63, v0, vcc
	v_add_co_u32_e32 v64, vcc, 0x40000, v64
	s_nop 1
	v_addc_co_u32_e32 v65, vcc, 0, v65, vcc
	global_store_dwordx2 v[64:65], v[62:63], off sc1

.LBB0_804:
	s_or_b64 exec, exec, s[12:13]
	s_nop 0
	v_pk_mul_f32 v[18:19], v[66:67], s[62:63] op_sel_hi:[1,0]
	v_pk_mul_f32 v[20:21], v[38:39], s[62:63] op_sel_hi:[1,0]
	v_cvt_pk_bf16_f32 v18, v18, v19
	v_cvt_pk_bf16_f32 v19, v20, v21
	v_pk_mul_f32 v[20:21], v[68:69], s[62:63] op_sel_hi:[1,0]
	s_nop 0
	v_pk_mul_f32 v[22:23], v[40:41], s[62:63] op_sel_hi:[1,0]
	v_cvt_pk_bf16_f32 v20, v20, v21
	v_cvt_pk_bf16_f32 v21, v22, v23
	v_pk_mul_f32 v[22:23], v[42:43], s[62:63] op_sel_hi:[1,0]
	v_pk_mul_f32 v[24:25], v[44:45], s[62:63] op_sel_hi:[1,0]
	v_cvt_pk_bf16_f32 v22, v22, v23
	v_cvt_pk_bf16_f32 v23, v24, v25
	v_pk_mul_f32 v[24:25], v[64:65], s[62:63] op_sel_hi:[1,0]
	s_nop 0
	v_pk_mul_f32 v[30:31], v[62:63], s[62:63] op_sel_hi:[1,0]
	v_lshl_add_u64 v[26:27], v[60:61], 0, s[94:95]
	s_mov_b64 s[12:13], 0x2800600
	v_cvt_pk_bf16_f32 v24, v24, v25
	v_cvt_pk_bf16_f32 v25, v30, v31
	v_lshl_add_u64 v[28:29], v[60:61], 0, s[12:13]
	global_store_dwordx4 v[26:27], v[22:25], off sc1
	global_store_dwordx4 v[28:29], v[18:21], off sc1
	s_and_saveexec_b64 s[12:13], s[8:9]
	s_cbranch_execz .LBB0_791
	v_cvt_pk_bf16_f32 v18, v70, v71
	v_cvt_pk_bf16_f32 v19, v34, v35
	v_cvt_pk_bf16_f32 v20, v72, v73
	v_cvt_pk_bf16_f32 v21, v74, v75
	global_store_dwordx4 v[58:59], v[18:21], off
	s_branch .LBB0_791

.LBB0_2260:
	s_or_b64 exec, exec, s[8:9]
	s_and_b64 vcc, exec, s[4:5]
	s_cbranch_vccnz .LBB0_2241
	v_pk_mul_f32 v[62:63], v[32:33], v[32:33]
	v_pk_mul_f32 v[68:69], v[30:31], v[30:31]
	v_mov_b32_e32 v71, v63
	v_mov_b32_e32 v70, v68
	v_pk_mov_b32 v[62:63], v[68:69], v[62:63] op_sel:[1,0]
	v_pk_mul_f32 v[68:69], v[28:29], v[28:29]
	v_pk_add_f32 v[62:63], v[62:63], v[70:71]
	v_pk_mul_f32 v[70:71], v[26:27], v[26:27]
	v_mov_b32_e32 v73, v69
	v_mov_b32_e32 v72, v70
	v_pk_mov_b32 v[68:69], v[70:71], v[68:69] op_sel:[1,0]
	v_mul_f32_e32 v61, v18, v18
	v_pk_add_f32 v[68:69], v[68:69], v[72:73]
	v_mul_f32_e32 v65, v19, v19
	v_pk_add_f32 v[62:63], v[62:63], v[62:63] op_sel:[0,1] op_sel_hi:[1,0]
	v_pk_add_f32 v[68:69], v[68:69], v[68:69] op_sel:[0,1] op_sel_hi:[1,0]
	v_mov_b32_e32 v63, v61
	v_mov_b32_e32 v69, v65
	v_pk_add_f32 v[62:63], v[62:63], v[68:69]
	v_mul_f32_e32 v68, v23, v23
	v_mul_f32_e32 v70, v25, v25
	v_mul_f32_e32 v67, v20, v20
	v_mul_f32_e32 v72, v21, v21
	v_pk_fma_f32 v[68:69], v[22:23], v[22:23], v[68:69] op_sel_hi:[1,1,0]
	v_pk_fma_f32 v[70:71], v[24:25], v[24:25], v[70:71] op_sel_hi:[1,1,0]
	s_load_dwordx2 s[8:9], s[0:1], 0x30
	v_mov_b32_e32 v69, v67
	v_mov_b32_e32 v71, v72
	v_pk_add_f32 v[68:69], v[68:69], v[70:71]
	v_add_u32_e32 v59, 9, v59
	v_pk_add_f32 v[62:63], v[62:63], v[68:69]
	v_mul_hi_i32_i24_e32 v69, 0x3000, v59
	v_mul_i32_i24_e32 v68, 0x3000, v59
	v_lshl_add_u64 v[68:69], s[18:19], 0, v[68:69]
	v_ashrrev_i32_e32 v59, 31, v58
	s_mov_b64 s[26:27], 0x1000
	s_waitcnt lgkmcnt(0)
	s_add_u32 s8, s8, 0x1000
	v_lshlrev_b64 v[82:83], 11, v[58:59]
	v_lshl_add_u64 v[58:59], v[68:69], 0, s[26:27]
	s_addc_u32 s9, s9, 0
	v_lshl_add_u64 v[68:69], v[68:69], 0, v[0:1]
	v_lshl_add_u64 v[78:79], v[58:59], 0, v[0:1]
	global_load_dwordx4 v[70:73], v0, s[8:9]
	global_load_dwordx4 v[74:77], v[68:69], off
	v_add_f32_e32 v61, v62, v63
	global_load_dwordx4 v[78:81], v[78:79], off
	ds_bpermute_b32 v62, v35, v61
	v_mov_b32_e32 v67, v1
	v_mov_b32_e32 v65, v1
	s_waitcnt lgkmcnt(0)
	v_add_f32_e32 v61, v61, v62
	ds_bpermute_b32 v62, v41, v61
	s_waitcnt lgkmcnt(0)
	v_add_f32_e32 v61, v61, v62
	ds_bpermute_b32 v62, v43, v61
	s_waitcnt lgkmcnt(0)
	v_add_f32_e32 v61, v61, v62
	ds_bpermute_b32 v62, v45, v61
	s_waitcnt lgkmcnt(0)
	v_add_f32_e32 v61, v61, v62
	ds_bpermute_b32 v62, v84, v61
	s_waitcnt lgkmcnt(0)
	v_add_f32_e32 v61, v61, v62
	ds_bpermute_b32 v62, v85, v61
	s_waitcnt lgkmcnt(0)
	v_add_f32_e32 v61, v61, v62
	v_fmamk_f32 v61, v61, 0x3a800000, v216
	v_cmp_gt_f32_e32 vcc, s33, v61
	v_mul_f32_e32 v62, 0x4b800000, v61
	s_nop 0
	v_cndmask_b32_e32 v61, v61, v62, vcc
	v_rsq_f32_e32 v61, v61
	s_nop 0
	v_mul_f32_e32 v62, 0x45800000, v61
	v_cndmask_b32_e32 v62, v61, v62, vcc
	v_pk_mul_f32 v[32:33], v[32:33], v[62:63] op_sel_hi:[1,0]
	v_pk_mul_f32 v[30:31], v[30:31], v[62:63] op_sel_hi:[1,0]
	v_pk_mul_f32 v[28:29], v[28:29], v[62:63] op_sel_hi:[1,0]
	v_pk_mul_f32 v[26:27], v[26:27], v[62:63] op_sel_hi:[1,0]
	v_pk_mul_f32 v[24:25], v[24:25], v[62:63] op_sel_hi:[1,0]
	v_pk_mul_f32 v[22:23], v[22:23], v[62:63] op_sel_hi:[1,0]
	v_mov_b32_e32 v61, v1
	v_pk_mul_f32 v[20:21], v[20:21], v[62:63] op_sel_hi:[1,0]
	v_pk_mul_f32 v[18:19], v[18:19], v[62:63] op_sel_hi:[1,0]
	s_waitcnt vmcnt(2)
	v_pk_mul_f32 v[30:31], v[70:71], v[30:31]
	v_pk_mul_f32 v[32:33], v[72:73], v[32:33]
	s_waitcnt vmcnt(0)
	v_pk_add_f32 v[70:71], v[80:81], 1.0 op_sel_hi:[1,0]
	v_pk_add_f32 v[72:73], v[78:79], 1.0 op_sel_hi:[1,0]
	v_pk_fma_f32 v[32:33], v[70:71], v[32:33], v[76:77]
	v_pk_fma_f32 v[30:31], v[72:73], v[30:31], v[74:75]
	v_cvt_pk_bf16_f32 v71, v32, v33
	v_cvt_pk_bf16_f32 v70, v30, v31
	v_lshl_add_u64 v[30:31], v[48:49], 0, v[82:83]
	global_store_dwordx2 v[30:31], v[70:71], off sc1
	v_lshl_add_u64 v[32:33], v[58:59], 0, v[66:67]
	global_load_dwordx4 v[70:73], v66, s[8:9]
	global_load_dwordx4 v[74:77], v[68:69], off offset:1024
	global_load_dwordx4 v[78:81], v[32:33], off
	s_waitcnt vmcnt(2)
	v_pk_mul_f32 v[26:27], v[70:71], v[26:27]
	v_pk_mul_f32 v[28:29], v[72:73], v[28:29]
	s_waitcnt vmcnt(0)
	v_pk_add_f32 v[32:33], v[80:81], 1.0 op_sel_hi:[1,0]
	v_pk_add_f32 v[66:67], v[78:79], 1.0 op_sel_hi:[1,0]
	v_pk_fma_f32 v[28:29], v[32:33], v[28:29], v[76:77]
	v_pk_fma_f32 v[26:27], v[66:67], v[26:27], v[74:75]
	v_lshl_add_u64 v[32:33], v[58:59], 0, v[64:65]
	v_cvt_pk_bf16_f32 v26, v26, v27
	v_cvt_pk_bf16_f32 v27, v28, v29
	global_store_dwordx2 v[30:31], v[26:27], off offset:512 sc1
	global_load_dwordx4 v[26:29], v64, s[8:9]
	s_nop 0
	global_load_dwordx4 v[70:73], v[68:69], off offset:2048
	global_load_dwordx4 v[64:67], v[32:33], off
	v_lshl_add_u64 v[32:33], v[58:59], 0, v[60:61]
	s_waitcnt vmcnt(2)
	v_pk_mul_f32 v[22:23], v[26:27], v[22:23]
	v_pk_mul_f32 v[24:25], v[28:29], v[24:25]
	s_waitcnt vmcnt(0)
	v_pk_add_f32 v[26:27], v[66:67], 1.0 op_sel_hi:[1,0]
	v_pk_add_f32 v[28:29], v[64:65], 1.0 op_sel_hi:[1,0]
	v_pk_fma_f32 v[24:25], v[26:27], v[24:25], v[72:73]
	v_pk_fma_f32 v[22:23], v[28:29], v[22:23], v[70:71]
	s_nop 0
	v_cvt_pk_bf16_f32 v22, v22, v23
	v_cvt_pk_bf16_f32 v23, v24, v25
	global_store_dwordx2 v[30:31], v[22:23], off offset:1024 sc1
	global_load_dwordx4 v[22:25], v60, s[8:9]
	s_nop 0
	global_load_dwordx4 v[26:29], v[68:69], off offset:3072
	global_load_dwordx4 v[58:61], v[32:33], off
	s_waitcnt vmcnt(2)
	v_pk_mul_f32 v[18:19], v[18:19], v[22:23]
	v_pk_mul_f32 v[20:21], v[20:21], v[24:25]
	s_waitcnt vmcnt(0)
	v_pk_add_f32 v[22:23], v[60:61], 1.0 op_sel_hi:[1,0]
	v_pk_add_f32 v[24:25], v[58:59], 1.0 op_sel_hi:[1,0]
	v_pk_fma_f32 v[20:21], v[20:21], v[22:23], v[28:29]
	v_pk_fma_f32 v[18:19], v[18:19], v[24:25], v[26:27]
	s_nop 0
	v_cvt_pk_bf16_f32 v18, v18, v19
	v_cvt_pk_bf16_f32 v19, v20, v21
	global_store_dwordx2 v[30:31], v[18:19], off offset:1536 sc1
	s_branch .LBB0_2241
